# extra K DMA piece moved from wave 0 to wave 2 so no wave issues more than 5 DMA pieces per tile
# speedup vs baseline: 1.0094x; 1.0085x over previous
; #define LAS __attribute__((address_space(3)))
; #define VLOAD(ks, DST) do { const LAS unsigned char* vp_ = Vb + (ks) * 32; \
;         _Pragma("unroll") for (int nb = 0; nb < NB; ++nb) DST[nb] = *(const LAS bf16x8*)(vp_ + nb * 32 * VTP); } while (0)
; #define PVMMA(SRC, PF) do { _Pragma("unroll") for (int nb = 0; nb < NB; ++nb) o[nb] = __builtin_amdgcn_mfma_f32_32x32x16_bf16(SRC[nb], PF, o[nb], 0, 0, 0); } while (0)
; #define SBAR_() __builtin_amdgcn_sched_barrier(0)
; template <int MODE, bool FROZEN = false>
; __device__ __forceinline__ bool attn_unit(LAS unsigned char* lds, const Params& p, int l, int ua, int ub) {
;     ...
;     for (int t = 0; t < NT; ++t) {
;         if (t + 2 < NT) {
; #pragma unroll
;             for (int i = 0; i < NKC; ++i) *(LAS u32x4*)(lds + kdst[i] + (t & 1) * KBUF) = kr[i];
;         }
;         if (t + 1 < NT) {
; #pragma unroll
;             for (int i = 0; i < NVC; ++i) { *(LAS u32x2*)(lds + vdst[i] + ((t + 1) & 1) * VBUF) = (u32x2){vr[i].x, vr[i].y}; *(LAS u32x2*)(lds + vdst[i] + ((t + 1) & 1) * VBUF + 16) = (u32x2){vr[i].z, vr[i].w}; }
;         }
;         {
;             const size_t advk = (size_t)min(t + 3, NT - 1) * 64 * NPROJ, advv = (size_t)min(t + 2, NT - 1) * 64;
; #pragma unroll
;             for (int i = 0; i < NKC; ++i) kr[i] = *(const u32x4*)(kvbase + advk + ksrc[i]);
; #pragma unroll
;             for (int i = 0; i < NVC; ++i) vr[i] = *(const u32x4*)(vtbase + advv + vsrc[i]);
;         }
;         f32x16 sA0 = sB0, sA1 = sB1;
;         const float c2 = cbB - m_run;
;         const LAS unsigned char* Vb = lds + OFF_V + (t & 1) * VBUF + vlane_off;
;         const LAS unsigned char* Kb = lds + OFF_K + ((t + 1) & 1) * KBUF + klane_off;
;     ...
;         bf16x8 kf0[4], kf1[4], va[NB], vb[NB], pf0, pf1; float ps0, ps1, ps2, ps3;
;         VLOAD(0, va);
;         EXPCVT(0, pf0, ps0);
;         SBAR_();
;         VLOAD(1, vb); PVMMA(va, pf0); EXPCVT(1, pf1, ps1); _Pragma("unroll") for (int g_ = 0; g_ < NB; ++g_) { __builtin_amdgcn_sched_group_barrier(0x008, 1, 0); __builtin_amdgcn_sched_group_barrier(0x100, 1, 0); __builtin_amdgcn_sched_group_barrier(0x400, 8 / NB, 0); __builtin_amdgcn_sched_group_barrier(0x002, 12 / NB, 0); } SBAR_();
.LBB0_117:
.LBB0_118:
	s_add_i32 s14, s4, 1
	s_bitcmp1_b32 s14, 0
	s_cselect_b32 s15, 0x4400, 0
	s_cselect_b32 s100, 0, 0x4800
	v_add_u32_e32 v194, s100, v101
	s_sub_i32 s5, 0x4400, s15
	s_min_i32 s10, s4, 0xfd
	s_mul_i32 s10, s10, 0x78000
	s_add_u32 s10, s34, s10
	s_addc_u32 s11, s35, 0
	s_add_u32 s10, s10, s99
	s_addc_u32 s11, s11, 0
	s_lshl_b32 s0, s14, 7
	s_add_u32 s0, s6, s0
	s_addc_u32 s1, s7, 0
	s_add_u32 s0, s0, s101
	s_addc_u32 s1, s1, 0
	ds_read_b128 v[112:115], v194 offset:34816
	ds_read_b128 v[170:173], v194 offset:39424
	ds_read_b128 v[174:177], v194 offset:44032
	ds_read_b128 v[178:181], v194 offset:48640
	v_exp_f32_e32 v103, v16
	v_exp_f32_e32 v104, v17
	v_mfma_f32_32x32x16_bf16 v[52:67], v[236:239], v[244:247], v[52:67]
	v_exp_f32_e32 v105, v18
	v_exp_f32_e32 v106, v19
	v_cvt_pk_bf16_f32 v16, v103, v104
	v_mfma_f32_32x32x16_bf16 v[36:51], v[218:221], v[244:247], v[36:51]
	s_add_i32 m0, s5, s98
	s_nop 0
	global_load_lds_dwordx4 v132, s[10:11]
	v_exp_f32_e32 v107, v20
	v_exp_f32_e32 v108, v21
	v_cvt_pk_bf16_f32 v17, v105, v106
	v_mfma_f32_32x32x16_bf16 v[84:99], v[222:225], v[244:247], v[84:99]
	s_add_i32 m0, m0, 0x400
	s_nop 0
	global_load_lds_dwordx4 v133, s[10:11]
	v_exp_f32_e32 v109, v22
	v_exp_f32_e32 v110, v23
	v_cvt_pk_bf16_f32 v18, v107, v108
	v_mfma_f32_32x32x16_bf16 v[68:83], v[248:251], v[244:247], v[68:83]
	s_cmp_lg_u32 s98, 0x1000
	s_cbranch_scc1 .Lkdma_skip
	s_add_i32 m0, s5, 0x4000
	s_nop 0
	global_load_lds_dwordx4 v134, s[10:11]
